# v22 + grid barrier protocol v2 (release counters per XCD, no returned top-level atomic, all 12 instances)
# baseline (speedup 1.0000x reference)
.LBB0_94:
	s_lshl_b32 s6, s48, 8
	s_add_u32 s6, s4, s6
	s_addc_u32 s7, s5, 0
	s_add_u32 s6, s6, 0x180000
	s_addc_u32 s7, s7, 0
	s_lshl_b32 s14, s48, 7
	s_add_u32 s14, s4, s14
	s_addc_u32 s15, s5, 0
	s_add_u32 s14, s14, 0x183600
	s_addc_u32 s15, s15, 0
	s_add_u32 s18, s4, 0x183600
	s_addc_u32 s19, s5, 0
	v_cvt_f32_u32_e32 v1, v2
	v_rcp_f32_e32 v1, v1
	v_mov_b32_e32 v5, 0
	s_mov_b32 s101, 0
.LXB2_REP_0:
	v_mov_b32_e32 v3, 1
	v_mov_b32_e32 v4, 0x1000
	global_atomic_add v3, v4, v3, s[6:7] offset:1024 sc0
	s_waitcnt vmcnt(0) lgkmcnt(0)
	v_cvt_f32_u32_e32 v4, v3
	v_add_f32_e32 v4, 0.5, v4
	v_mul_f32_e32 v4, v4, v1
	v_cvt_u32_f32_e32 v4, v4
	v_add_u32_e32 v3, 1, v3
	v_add_u32_e32 v4, 1, v4
	v_mul_lo_u32 v1, v4, v2
	v_mul_lo_u32 v4, v4, v0
	s_nop 0
	v_readfirstlane_b32 s8, v4
	v_readfirstlane_b32 s9, v1
	v_readfirstlane_b32 s10, v3
	v_cvt_f32_u32_e32 v1, v2
	v_rcp_f32_e32 v1, v1
	s_cmp_lg_u32 s9, s10
	s_cbranch_scc1 .LXB2_POLL_0
	buffer_wbl2 sc1
	s_waitcnt vmcnt(0)
	s_mov_b64 exec, 0xffff
	v_lshlrev_b32_e32 v4, 7, v248
	v_mov_b32_e32 v3, 1
	global_atomic_add v4, v3, s[18:19]
	s_mov_b64 exec, 1

.LXB2_SPIN_0:
	global_load_dword v3, v5, s[14:15] sc1
	s_waitcnt vmcnt(0)
	v_readfirstlane_b32 s9, v3
	s_cmp_ge_u32 s9, s8
	s_cbranch_scc1 .LXB2_ACQ_0
	s_sleep 1
	s_add_i32 s16, s16, 1
	s_cmp_lt_u32 s16, 0x200000
	s_cbranch_scc1 .LXB2_SPIN_0

.LBB0_280:
	s_lshl_b32 s6, s49, 8
	s_add_u32 s6, s4, s6
	s_addc_u32 s7, s5, 0
	s_add_u32 s6, s6, 0x180000
	s_addc_u32 s7, s7, 0
	s_lshl_b32 s14, s49, 7
	s_add_u32 s14, s4, s14
	s_addc_u32 s15, s5, 0
	s_add_u32 s14, s14, 0x183600
	s_addc_u32 s15, s15, 0
	s_add_u32 s18, s4, 0x183600
	s_addc_u32 s19, s5, 0
	v_cvt_f32_u32_e32 v1, v2
	v_rcp_f32_e32 v1, v1
	v_mov_b32_e32 v5, 0
	s_mov_b32 s101, 0

.LBB0_412:
	s_lshl_b32 s6, s50, 8
	s_add_u32 s6, s4, s6
	s_addc_u32 s7, s5, 0
	s_add_u32 s6, s6, 0x180000
	s_addc_u32 s7, s7, 0
	s_lshl_b32 s14, s50, 7
	s_add_u32 s14, s4, s14
	s_addc_u32 s15, s5, 0
	s_add_u32 s14, s14, 0x183600
	s_addc_u32 s15, s15, 0
	s_add_u32 s18, s4, 0x183600
	s_addc_u32 s19, s5, 0
	v_cvt_f32_u32_e32 v1, v2
	v_rcp_f32_e32 v1, v1
	v_mov_b32_e32 v5, 0
	s_mov_b32 s101, 0

.LXB2_ACQ_11:
	s_waitcnt vmcnt(0)
	buffer_inv sc1
	s_waitcnt vmcnt(0)

	s_mov_b64 s[4:5], 0
	s_getpc_b64 s[98:99]
.Lpost_getpc0:
	s_add_u32 s98, s98, (.LBB0_133-.Lpost_getpc0)&4294967295
	s_addc_u32 s99, s99, (.LBB0_133-.Lpost_getpc0)>>32
	s_setpc_b64 s[98:99]

